# safety: P and HID share a workspace region, so second-half G1 checks once (before its first P store) that every workgroup has finished first-half G6; counter bumped where the removed grid barrier was
# speedup vs baseline: 1.0012x; 1.0012x over previous
; __global__ void __launch_bounds__(512, 2) fwd_mega(Args a) {
;     ...
;     unsigned char* ws = a.ws;
;     float* ada = (float*)(ws + WS_ADA); unsigned* ctl = (unsigned*)(ws + WS_CTL); float* rowss = (float*)(ws + WS_ROWSS); float* bias2 = (float*)(ws + WS_BIAS2);
;     bf16* WinT = (bf16*)(ws + WS_WIN); bf16* WattT = (bf16*)(ws + WS_WATT); bf16* WmlT = (bf16*)(ws + WS_WML); bf16* WoutT = (bf16*)(ws + WS_WOUT); bf16* Wff1T = (bf16*)(ws + WS_WFF1); bf16* Wff2T = (bf16*)(ws + WS_WFF2);
;     float* IFg = (float*)(ws + WS_IF); bf16* U = (bf16*)(ws + WS_U); bf16* P = (bf16*)(ws + WS_P); bf16* HID = (bf16*)(ws + WS_HID); bf16* OG = (bf16*)(ws + WS_OG); bf16* YPRE = (bf16*)(ws + WS_YPRE);
;     float* LSE = (float*)(ws + WS_LSE); bf16* Hb = (bf16*)(ws + WS_H); bf16* ATT = (bf16*)(ws + WS_ATT);
.LBB0_142:
	s_or_b64 exec, exec, s[0:1]
	v_readlane_b32 s12, v251, 8
	v_readlane_b32 s13, v251, 9
	s_add_u32 s0, s12, 0xc0000
	v_readlane_b32 s14, v251, 10
	v_readlane_b32 s15, v251, 11
	v_writelane_b32 v251, s0, 46
	s_addc_u32 s0, s13, 0
	v_writelane_b32 v251, s0, 47
	s_add_u32 s0, s12, 0x100000
	v_writelane_b32 v251, s0, 48
	s_addc_u32 s0, s13, 0
	v_writelane_b32 v251, s0, 49
	s_add_u32 s0, s12, 0x2c00000
	v_writelane_b32 v251, s0, 50
	s_addc_u32 s0, s13, 0
	v_writelane_b32 v251, s0, 51
	s_add_u32 s0, s12, 0x3000000
	v_writelane_b32 v251, s0, 52
	s_addc_u32 s0, s13, 0
	s_add_u32 s86, s12, 0xb000000
	s_addc_u32 s87, s13, 0
	s_add_u32 s88, s12, 0x31000000
	s_addc_u32 s89, s13, 0
	s_add_u32 s90, s12, 0x37000000
	s_addc_u32 s91, s13, 0
	s_add_u32 s16, s12, 0x37200000
	s_addc_u32 s17, s13, 0
	s_add_u32 s92, s12, 0x3b200000
	s_addc_u32 s93, s13, 0
	s_cmpk_lt_i32 s51, 0x1300
	v_writelane_b32 v251, s0, 53
	s_cselect_b64 s[0:1], -1, 0
	v_writelane_b32 v251, s0, 54
	s_ashr_i32 s94, s51, 31
	s_ashr_i32 s95, s14, 31
	v_writelane_b32 v251, s1, 55
	s_lshr_b32 s0, s94, 29
	s_add_i32 s0, s51, s0
	s_ashr_i32 s1, s0, 3
	s_and_b32 s0, s0, -8
	s_sub_i32 s0, s51, s0
	s_add_u32 s2, s12, 0x1500000
	s_addc_u32 s3, s13, 0
	v_writelane_b32 v251, s2, 56
	s_cmpk_lt_i32 s51, 0x80
	v_mov_b32_e32 v1, 0
	v_writelane_b32 v251, s3, 57
	s_cselect_b64 s[2:3], -1, 0
	v_writelane_b32 v251, s2, 58
	v_mov_b32_e32 v250, 0x2000
	v_mov_b32_e32 v189, 1
	v_writelane_b32 v251, s3, 59
	s_lshl_b32 s2, s0, 4
	s_add_u32 s4, s12, 0x1540000
	s_addc_u32 s5, s13, 0
	v_writelane_b32 v251, s4, 60
	v_mov_b32_e32 v192, 0x358637bd
	v_mov_b32_e32 v193, 0xf149f2ca
	v_writelane_b32 v251, s5, 61
	s_add_u32 s4, s12, 0x1500080
	s_addc_u32 s5, s13, 0
	v_writelane_b32 v251, s4, 62
	v_mbcnt_hi_u32_b32 v194, -1, v70
	v_mov_b32_e32 v195, 0x41b17218
	v_writelane_b32 v251, s5, 63
	s_add_u32 s4, s12, 0x1540080
	s_addc_u32 s5, s13, 0
	v_writelane_b32 v252, s4, 0
	v_mov_b64_e32 v[166:167], 0x80
	v_mov_b64_e32 v[168:169], 0x7f
	v_writelane_b32 v252, s5, 1
	s_add_u32 s4, s12, 0xc4200
	s_addc_u32 s5, s13, 0
	s_add_u32 s96, s12, 0xc4400
	s_addc_u32 s97, s13, 0
	s_add_u32 s54, s12, 0xc4500
	s_addc_u32 s55, s13, 0
	s_add_u32 s56, s12, 0xc4600
	s_addc_u32 s57, s13, 0
	s_add_u32 s58, s12, 0xc4700
	s_addc_u32 s59, s13, 0
	s_add_u32 s60, s12, 0xc4800
	s_addc_u32 s61, s13, 0
	s_add_u32 s64, s12, 0xc4900
	v_writelane_b32 v252, s4, 2
	s_addc_u32 s65, s13, 0
	v_mov_b32_e32 v240, v1
	v_writelane_b32 v252, s5, 3
	s_add_u32 s4, s12, 0xc4a00
	s_addc_u32 s5, s13, 0
	v_writelane_b32 v252, s4, 4
	v_mov_b32_e32 v241, v1
	v_mov_b32_e32 v242, v1
	v_writelane_b32 v252, s5, 5
	s_add_u32 s4, s12, 0xc4b00
	s_addc_u32 s5, s13, 0
	v_writelane_b32 v252, s4, 6
	v_mov_b32_e32 v243, v1
	v_bfrev_b32_e32 v196, 0.5
	v_writelane_b32 v252, s5, 7
	s_add_u32 s4, s12, 0xc4c00
	s_addc_u32 s5, s13, 0
	v_writelane_b32 v252, s4, 8
	v_mov_b32_e32 v197, 0x12000000
	v_mov_b64_e32 v[170:171], 0x200
	v_writelane_b32 v252, s5, 9
	s_add_u32 s4, s12, 0xc4d00
	s_addc_u32 s5, s13, 0
	v_writelane_b32 v252, s4, 10
	v_mov_b64_e32 v[172:173], 0x1ff
	v_mov_b32_e32 v198, 0x80
	v_writelane_b32 v252, s5, 11
	s_add_u32 s4, s12, 0xc4e00
	s_addc_u32 s5, s13, 0
	v_writelane_b32 v252, s4, 12
	v_mov_b64_e32 v[174:175], 0x800
	v_mov_b64_e32 v[176:177], 0x7ff
	v_writelane_b32 v252, s5, 13
	s_add_u32 s4, s12, 0xc4f00
	s_addc_u32 s5, s13, 0
	v_writelane_b32 v252, s4, 14
	s_mov_b64 s[84:85], 0x80
	s_waitcnt lgkmcnt(0)
	v_writelane_b32 v252, s5, 15
	s_add_u32 s4, s12, 0xc5000
	s_addc_u32 s5, s13, 0
	v_writelane_b32 v252, s4, 16
	s_barrier
	s_nop 0
	v_writelane_b32 v252, s5, 17
	s_add_u32 s4, s12, 0xc5100
	s_addc_u32 s5, s13, 0
	v_writelane_b32 v252, s4, 18
	s_nop 1
	v_writelane_b32 v252, s5, 19
	s_add_u32 s4, s12, 0xc5200
	s_addc_u32 s5, s13, 0
	v_writelane_b32 v252, s4, 20
	s_nop 1
	v_writelane_b32 v252, s5, 21
	s_add_u32 s4, s12, 0xc5300
	s_addc_u32 s5, s13, 0
	v_writelane_b32 v252, s4, 22
	s_nop 1
	v_writelane_b32 v252, s5, 23
	s_add_u32 s4, s12, 0xc7400
	s_addc_u32 s5, s13, 0
	v_writelane_b32 v252, s4, 24
	s_nop 1
	v_writelane_b32 v252, s5, 25
	s_add_u32 s4, s12, 0xc7500
	s_addc_u32 s5, s13, 0
	s_lshl_b32 s3, s51, 9
	s_add_u32 s30, s12, 0x33000000
	s_addc_u32 s31, s13, 0
	s_add_u32 s48, s12, 0x35000000
	v_writelane_b32 v252, s4, 26
	s_addc_u32 s49, s13, 0
	s_lshl_b32 s50, s14, 9
	v_writelane_b32 v252, s5, 27
	s_cmpk_lt_i32 s51, 0x200
	v_writelane_b32 v252, s3, 28
	s_cselect_b64 s[4:5], -1, 0
	s_lshl_b32 s3, s0, 6
	v_writelane_b32 v252, s4, 29
	s_cmpk_lt_i32 s51, 0x800
	s_nop 0
	v_writelane_b32 v252, s5, 30
	s_cselect_b64 s[4:5], -1, 0
	v_writelane_b32 v252, s4, 31
	s_nop 1
	v_writelane_b32 v252, s5, 32
	s_lshl_b32 s4, s0, 8
	s_add_u32 s5, s12, 0x5000
	v_writelane_b32 v252, s5, 33
	s_addc_u32 s5, s13, 0
	v_writelane_b32 v252, s5, 34
	s_cmp_lt_i32 s0, 0
	s_mul_i32 s5, s0, 17
	s_cselect_b32 s2, s5, s2
	s_mul_i32 s5, s0, 0x41
	s_cselect_b32 s3, s5, s3
	s_movk_i32 s5, 0x261
	s_cselect_b32 s5, s5, 0x260
	s_mul_i32 s5, s0, s5
	s_mulk_i32 s0, 0x101
	s_cselect_b32 s8, s0, s4
	s_add_i32 s5, s5, s1
	s_mul_hi_i32 s0, s5, 0x6bca1af3
	s_lshr_b32 s4, s0, 31
	s_ashr_i32 s0, s0, 7
	s_add_i32 s0, s0, s4
	s_mul_i32 s4, s0, 0x130
	s_sub_i32 s4, s5, s4
	s_bfe_u32 s5, s4, 0x3001c
	s_add_i32 s5, s4, s5
	s_and_b32 s6, s5, 0xfff8
	s_add_i32 s3, s3, s1
	s_sub_i32 s4, s4, s6
	s_ashr_i32 s6, s3, 31
	s_lshr_b32 s6, s6, 27
	s_add_i32 s6, s3, s6
	s_and_b32 s7, s6, 0xffe0
	s_sub_i32 s3, s3, s7
	s_bfe_i32 s7, s3, 0x80000
	s_bfe_u32 s7, s7, 0x3000c
	s_add_i32 s7, s3, s7
	s_and_b32 s9, s7, 0xf8
	s_lshl_b32 s0, s0, 3
	s_sext_i32_i16 s4, s4
	s_sub_i32 s3, s3, s9
	s_add_i32 s12, s0, s4
	s_add_i32 s10, s2, s1
;     __host__ __device__ bool next(int i, Unit& u) const {
;         const long L = (long)i * G + c; if (L >= nwg) return false;
;         int wgid = (int)L; { const int q = nwg / NXCD, r = nwg % NXCD, xcd = wgid % NXCD, off = wgid / NXCD; wgid = (xcd < r ? xcd * (q + 1) : r * (q + 1) + (xcd - r) * q) + off; }
;         const int nig = WGM * nN, gid = wgid / nig, fm = gid * WGM, gsz = (nM - fm) < WGM ? (nM - fm) : WGM;
;         u.pm = fm + ((wgid % nig) % gsz); u.pn = (wgid % nig) / gsz; return true;
;     }
; template <class Epi, class Sched, bool ALIGN_EPI = false, bool SP2 = false>
; __device__ __forceinline__ void gemm_phase(PG8_LAS unsigned char* lds, const Gemm g, const Sched& S, const Epi& E) {
;     ...
;     const char* cA = (const char*)g.A + (size_t)cur.pm * tstep; const char* cB = (const char*)g.Bt + (size_t)cur.pn * tstep;
	s_ashr_i32 s0, s6, 5
	s_bfe_i32 s2, s7, 0x80000
	s_lshl_b32 s0, s0, 3
	s_sext_i32_i16 s2, s2
	s_sext_i32_i8 s3, s3
	s_add_i32 s18, s0, s3
	s_ashr_i32 s0, s2, 3
	s_sext_i32_i16 s5, s5
	v_writelane_b32 v252, s0, 35
	s_lshr_b32 s0, s2, 3
	s_bfe_i64 s[6:7], s[0:1], 0x100000
	s_ashr_i32 s0, s5, 3
	v_writelane_b32 v252, s0, 36
	s_mov_b32 s2, s10
	s_ashr_i32 s11, s10, 31
	v_writelane_b32 v252, s2, 37
	s_ashr_i32 s19, s18, 31
	s_lshr_b32 s0, s5, 3
	v_writelane_b32 v252, s3, 38
	s_lshl_b64 s[2:3], s[10:11], 19
	v_writelane_b32 v252, s2, 39
	s_lshl_b64 s[4:5], s[6:7], 18
	v_readlane_b32 s10, v251, 34
	v_writelane_b32 v252, s3, 40
	s_lshl_b64 s[2:3], s[18:19], 18
	v_readlane_b32 s11, v251, 35
	s_add_u32 s4, s10, s4
	s_addc_u32 s5, s11, s5
	s_add_u32 s10, s4, 0x20000
	s_addc_u32 s11, s5, 0
	v_writelane_b32 v252, s10, 41
	s_add_u32 s2, s92, s2
	s_addc_u32 s3, s93, s3
	v_writelane_b32 v252, s11, 42
	s_add_u32 s10, s2, 0x20000
	v_writelane_b32 v252, s2, 43
	s_addc_u32 s11, s3, 0
	s_nop 0
	v_writelane_b32 v252, s3, 44
	v_writelane_b32 v252, s10, 45
	s_add_u32 s2, s4, 0x20080
	s_nop 0
	v_writelane_b32 v252, s11, 46
	v_writelane_b32 v252, s4, 47
	s_addc_u32 s3, s5, 0
	v_readlane_b32 s10, v251, 36
	v_writelane_b32 v252, s5, 48
	v_writelane_b32 v252, s2, 49
	s_lshl_b64 s[4:5], s[6:7], 19
	v_readlane_b32 s11, v251, 37
	v_writelane_b32 v252, s3, 50
	s_lshl_b64 s[2:3], s[18:19], 19
	s_add_u32 s10, s10, s4
	s_addc_u32 s11, s11, s5
	s_add_u32 s20, s10, 0x40000
	s_addc_u32 s21, s11, 0
	v_writelane_b32 v252, s20, 51
	s_nop 1
	v_writelane_b32 v252, s21, 52
	v_writelane_b32 v252, s16, 53
	s_add_u32 s16, s16, s2
	v_writelane_b32 v252, s17, 54
	s_addc_u32 s17, s17, s3
	s_add_u32 s20, s16, 0x40000
	v_writelane_b32 v252, s16, 55
	s_addc_u32 s21, s17, 0
	s_nop 0
	v_writelane_b32 v252, s17, 56
	v_writelane_b32 v252, s20, 57
	s_add_u32 s16, s10, 0x40080
	s_nop 0
	v_writelane_b32 v252, s21, 58
	v_writelane_b32 v252, s10, 59
	s_addc_u32 s17, s11, 0
	s_add_i32 s1, s8, s1
	s_ashr_i32 s8, s1, 31
	s_lshr_b32 s8, s8, 25
	s_add_i32 s8, s1, s8
	s_and_b32 s9, s8, 0xff80
	s_sub_i32 s1, s1, s9
	s_bfe_i32 s9, s1, 0x80000
	s_bfe_u32 s9, s9, 0x3000c
	s_add_i32 s9, s1, s9
	v_writelane_b32 v252, s11, 60
	s_and_b32 s10, s9, 0xf8
	s_sub_i32 s1, s1, s10
	s_ashr_i32 s8, s8, 7
	v_writelane_b32 v252, s16, 61
	s_lshl_b32 s8, s8, 3
	s_sext_i32_i8 s1, s1
	v_writelane_b32 v252, s17, 62
	s_add_i32 s16, s8, s1
	s_bfe_i32 s9, s9, 0x80000
	s_mov_b32 s10, s16
	s_sext_i32_i16 s9, s9
	s_ashr_i32 s17, s16, 31
	v_writelane_b32 v253, s10, 0
	s_lshr_b32 s8, s9, 3
	s_ashr_i32 s1, s9, 3
	v_writelane_b32 v253, s11, 1
	s_lshl_b64 s[10:11], s[16:17], 19
	s_bfe_i64 s[8:9], s[8:9], 0x100000
	v_writelane_b32 v253, s10, 2
	s_lshl_b64 s[8:9], s[8:9], 19
	v_writelane_b32 v252, s1, 63
	v_writelane_b32 v253, s11, 3
	v_readlane_b32 s10, v251, 40
	v_readlane_b32 s11, v251, 41
	s_add_u32 s8, s10, s8
	s_addc_u32 s9, s11, s9
	s_add_u32 s10, s8, 0x40000
	s_addc_u32 s11, s9, 0
	v_writelane_b32 v253, s10, 4
	s_nop 1
	v_writelane_b32 v253, s11, 5
	s_add_u32 s10, s8, 0x40080
	v_writelane_b32 v253, s8, 6
	s_addc_u32 s11, s9, 0
	s_lshl_b64 s[6:7], s[6:7], 21
	v_writelane_b32 v253, s9, 7
	v_writelane_b32 v253, s10, 8
	s_mov_b32 s8, s18
	s_nop 0
	v_writelane_b32 v253, s11, 9
	v_writelane_b32 v253, s8, 10
	v_readlane_b32 s10, v251, 42
	v_readlane_b32 s11, v251, 43
	v_writelane_b32 v253, s9, 11
	s_lshl_b64 s[8:9], s[18:19], 21
	s_add_u32 s6, s10, s6
	s_addc_u32 s7, s11, s7
	s_add_u32 s10, s6, 0x100000
	s_addc_u32 s11, s7, 0
	v_writelane_b32 v253, s10, 12
	s_add_u32 s8, s86, s8
	s_addc_u32 s9, s87, s9
	v_writelane_b32 v253, s11, 13
	s_add_u32 s10, s8, 0x100000
	v_writelane_b32 v253, s8, 14
	s_addc_u32 s11, s9, 0
	s_nop 0
	v_writelane_b32 v253, s9, 15
	v_writelane_b32 v253, s10, 16
	s_add_u32 s8, s6, 0x100080
	s_nop 0
	v_writelane_b32 v253, s11, 17
	v_writelane_b32 v253, s6, 18
	s_addc_u32 s9, s7, 0
	s_ashr_i32 s13, s12, 31
	v_writelane_b32 v253, s7, 19
	v_writelane_b32 v253, s8, 20
	s_mov_b32 s6, s12
	s_bfe_i64 s[0:1], s[0:1], 0x100000
	v_writelane_b32 v253, s9, 21
	v_writelane_b32 v253, s6, 22
	s_lshl_b64 s[0:1], s[0:1], 19
	s_mov_b64 s[10:11], s[62:63]
	v_writelane_b32 v253, s7, 23
	s_lshl_b64 s[6:7], s[12:13], 19
	v_writelane_b32 v253, s6, 24
	s_nop 1
	v_writelane_b32 v253, s7, 25
	v_readlane_b32 s6, v251, 32
	v_readlane_b32 s7, v251, 33
	s_add_u32 s0, s6, s0
	s_addc_u32 s1, s7, s1
	s_add_u32 s6, s0, 0x40000
	s_addc_u32 s7, s1, 0
	v_writelane_b32 v253, s6, 26
	s_nop 1
; #define LAS __attribute__((address_space(3)))
; __global__ void __launch_bounds__(512, 2) fwd_mega(Args a) {
;     ...
;     volatile LAS unsigned* bst = (volatile LAS unsigned*)(lds + LDS_BYTES - 16);
;     if (threadIdx.x == 0) { bst[0] = 0u; bst[1] = 0u; }
;     __syncthreads();
;     (void)xcd_barrier_post(ctl + 4096, bst);
	v_writelane_b32 v253, s7, 27
	s_add_u32 s6, s0, 0x40080
	v_writelane_b32 v253, s0, 28
	s_addc_u32 s7, s1, 0
	s_nop 0
	v_writelane_b32 v253, s1, 29
	v_readlane_b32 s0, v251, 38
	v_readlane_b32 s1, v251, 39
	s_add_u32 s4, s0, s4
	s_addc_u32 s5, s1, s5
	v_writelane_b32 v253, s6, 30
	s_add_u32 s0, s4, 0x40000
	s_addc_u32 s1, s5, 0
	v_writelane_b32 v253, s7, 31
	v_writelane_b32 v253, s0, 32
	s_add_u32 s2, s88, s2
	s_addc_u32 s3, s89, s3
	v_writelane_b32 v253, s1, 33
	s_mul_i32 s0, s15, s14
	s_mul_i32 s0, s0, s33
	v_writelane_b32 v253, s0, 34
	s_add_u32 s0, s2, 0x40000
	v_writelane_b32 v253, s2, 35
	s_addc_u32 s1, s3, 0
	s_nop 0
	v_writelane_b32 v253, s3, 36
	v_writelane_b32 v253, s0, 37
	s_mov_b32 s2, 0
	s_nop 0
	v_writelane_b32 v253, s1, 38
	s_add_u32 s0, s4, 0x40080
	v_writelane_b32 v253, s4, 39
	s_addc_u32 s1, s5, 0
	s_bitcmp1_b32 s51, 0
	v_writelane_b32 v253, s5, 40
	v_writelane_b32 v253, s0, 41
	s_nop 1
	v_writelane_b32 v253, s1, 42
	s_cselect_b64 s[0:1], -1, 0
	v_writelane_b32 v253, s0, 43
	s_bitcmp1_b32 s14, 0
	s_nop 0
	v_writelane_b32 v253, s1, 44
	s_mov_b32 s0, s14
	v_writelane_b32 v253, s0, 45
	s_cselect_b64 s[0:1], -1, 0
	v_writelane_b32 v253, s0, 46
	s_nop 1
	v_writelane_b32 v253, s1, 47
	s_lshl_b32 s0, s51, 12
	v_writelane_b32 v253, s0, 48
	s_lshl_b32 s0, s14, 12
	v_writelane_b32 v253, s0, 49
	s_add_i32 s0, 0, 0x23ff0
	v_writelane_b32 v253, s0, 50
	s_add_i32 s0, 0, 0x23ff4
	v_writelane_b32 v253, s0, 51
	s_add_i32 s0, 0, 0xc800
	v_writelane_b32 v253, s0, 52
	s_add_i32 s0, 0, 0x13300
	v_writelane_b32 v253, s0, 53
	s_add_i32 s0, 0, 0x12b00
	v_writelane_b32 v253, s0, 54
	s_add_i32 s0, 0, 0x11d00
	v_writelane_b32 v253, s0, 55
	s_add_i32 s0, 0, 0x12600
	v_writelane_b32 v253, s0, 56
	s_add_i32 s0, 0, 0x11e00
	v_writelane_b32 v253, s0, 57
	s_add_i32 s0, 0, 0x11c00
	v_writelane_b32 v253, s0, 58
	s_add_i32 s0, 0, 0x11c20
	v_writelane_b32 v253, s0, 59
	s_add_i32 s0, 0, 0x11c40
	v_writelane_b32 v253, s0, 60
	s_add_i32 s0, 0, 0x11c60
	v_writelane_b32 v253, s0, 61
	s_add_i32 s0, 0, 0x11c80
	v_writelane_b32 v253, s0, 62
	s_add_i32 s0, 0, 0x11ca0
	v_writelane_b32 v253, s0, 63
	s_add_i32 s0, 0, 0x11cc0
	v_writelane_b32 v254, s0, 0
	s_add_i32 s0, 0, 0x11ce0
	v_writelane_b32 v254, s0, 1
	s_add_i32 s0, 0, 0x13600
	v_writelane_b32 v254, s0, 2
	s_add_i32 s0, 0, 0x9694
	v_writelane_b32 v254, s0, 3
	s_mov_b64 s[0:1], -1
	v_writelane_b32 v254, s0, 4
	s_mov_b64 s[14:15], s[66:67]
	s_nop 0
	v_writelane_b32 v254, s1, 5
	s_mov_b32 s1, 0
	v_writelane_b32 v254, s0, 6
	s_nop 1
	v_writelane_b32 v254, s1, 7
	s_mov_b64 s[0:1], s[52:53]
	v_writelane_b32 v254, s0, 8
	s_nop 1
	v_writelane_b32 v254, s1, 9
	v_writelane_b32 v254, s2, 10
	v_writelane_b32 v254, s3, 11
	v_writelane_b32 v254, s4, 12
	v_writelane_b32 v254, s5, 13
	v_writelane_b32 v254, s6, 14
	v_writelane_b32 v254, s7, 15
	v_writelane_b32 v254, s8, 16
	v_writelane_b32 v254, s9, 17
	v_writelane_b32 v254, s10, 18
	v_writelane_b32 v254, s11, 19
	v_writelane_b32 v254, s12, 20
	v_writelane_b32 v254, s13, 21
	v_writelane_b32 v254, s14, 22
	v_writelane_b32 v254, s15, 23
	v_writelane_b32 v254, s54, 24
	s_nop 1
	v_writelane_b32 v254, s55, 25
	v_writelane_b32 v254, s56, 26
	s_nop 1
	v_writelane_b32 v254, s57, 27
	v_writelane_b32 v254, s58, 28
	s_nop 1
	v_writelane_b32 v254, s59, 29
	v_writelane_b32 v254, s60, 30
	s_nop 1
	v_writelane_b32 v254, s61, 31
	v_writelane_b32 v254, s64, 32
	s_nop 1
	v_writelane_b32 v254, s65, 33
	v_writelane_b32 v254, s30, 34
	s_nop 1
	v_writelane_b32 v254, s31, 35
	v_writelane_b32 v254, s48, 36
	s_nop 1
	v_writelane_b32 v254, s49, 37
	v_writelane_b32 v254, s50, 38
	v_writelane_b32 v254, s51, 39
	v_writelane_b32 v254, s86, 40
	s_nop 1
	v_writelane_b32 v254, s87, 41
	v_writelane_b32 v254, s88, 42
	s_nop 1
	v_writelane_b32 v254, s89, 43
	v_writelane_b32 v254, s90, 44
	s_nop 1
	v_writelane_b32 v254, s91, 45
	v_writelane_b32 v254, s92, 46
	s_nop 1
	v_writelane_b32 v254, s93, 47
	v_writelane_b32 v254, s94, 48
	v_writelane_b32 v254, s95, 49
	v_writelane_b32 v254, s96, 50
	s_nop 1
	v_writelane_b32 v254, s97, 51
	s_getreg_b32 s98, hwreg(HW_REG_XCC_ID, 0, 4)
	s_lshl_b32 s98, 1, s98
	v_mov_b32_e32 v0, s98
	s_and_b32 s99, s51, 7
	s_lshl_b32 s99, s99, 2
	v_readlane_b32 s100, v252, 26
	v_readlane_b32 s101, v252, 27
	s_add_u32 s100, s100, s99
	s_addc_u32 s101, s101, 0
	v_cmp_eq_u32_e32 vcc, 0, v188
	s_and_saveexec_b64 s[98:99], vcc
	s_nop 3
	global_atomic_or v1, v0, s[100:101] offset:32
	s_or_b64 exec, exec, s[98:99]
	v_writelane_b32 v255, 0, 48
	s_branch .LBB0_146

; __global__ void __launch_bounds__(512, 2) fwd_mega(Args a) {
;     ...
;         { pg8::Gemm g{U + (size_t)grow0 * 1024, WinT, TH, 38 * 256, 1024}; pg8::StaticOrder S; S.init(TH, 38 * 256, G, bx);
;           EpiInProj E{P, IFg + (size_t)grow0 * 16, a.in[7]};
;           pg8::gemm_phase<EpiInProj, pg8::StaticOrder, true, true>(lds, g, S, E); }
.LBB0_159:
	v_readlane_b32 s98, v254, 4
	v_readlane_b32 s99, v255, 48
	s_nop 0
	s_or_b32 s98, s98, s99
	s_cmp_lg_u32 s98, 0
	s_cbranch_scc1 .Lphg_done
	v_readlane_b32 s100, v252, 26
	v_readlane_b32 s101, v252, 27
	s_mov_b32 s99, 0
	s_nop 3
.Lphg_spin:
	global_load_dword v207, v1, s[100:101] offset:112 sc1
	s_waitcnt vmcnt(0)
	v_readfirstlane_b32 s98, v207
	s_cmp_ge_u32 s98, 0x100
	s_cbranch_scc1 .Lphg_ok
	s_sleep 1
	s_add_i32 s99, s99, 1
	s_cmp_lt_u32 s99, 0x8000
	s_cbranch_scc1 .Lphg_spin
.Lphg_ok:
	v_writelane_b32 v255, 1, 48

; #define GBAR() do { XcdBarrier xb_; xb_.bar = (unsigned*)(a.ws + WS_CTL) + 4096; xb_.x = xb_xcc_id(); xb_.st = (volatile LAS unsigned*)(lds + LDS_BYTES - 16); xcd_barrier(xb_); } while (0)
; __global__ void __launch_bounds__(512, 2) fwd_mega(Args a) {
;     ...
;         GBAR();
;         { pg8::Gemm g{HID, Wff2T, TH, 1024, 4096}; pg8::StaticOrder S; S.init(TH, 1024, G, bx);
;           EpiResid E{out + (size_t)grow0 * 1024, out + (size_t)grow0 * 1024, ada + 5120, grow0};
;           pg8::gemm_phase<EpiResid, pg8::StaticOrder, true, true>(lds, g, S, E); }
;         if (hb == 0) GBAR();
;     }
.LBB0_819:
	v_readlane_b32 s2, v254, 4
	v_readlane_b32 s3, v254, 5
	s_mov_b64 s[0:1], -1
	s_and_b64 vcc, exec, s[2:3]
	s_cbranch_vccz .LBB0_145
	s_getreg_b32 s2, hwreg(HW_REG_XCC_ID, 0, 4)
	s_waitcnt vmcnt(0)
	s_barrier
	v_cmp_eq_u32_e32 vcc, 0, v188
	s_and_saveexec_b64 s[98:99], vcc
	v_readlane_b32 s100, v252, 26
	v_readlane_b32 s101, v252, 27
	s_nop 4
	global_atomic_add v1, v189, s[100:101] offset:112
	s_or_b64 exec, exec, s[98:99]
	s_mov_b64 s[0:1], exec
	s_branch .LBB0_144
	v_readlane_b32 s4, v251, 12
	v_readlane_b32 s5, v251, 13
	s_and_b64 s[4:5], s[0:1], s[4:5]
	s_mov_b64 exec, s[4:5]
	s_cbranch_execz .LBB0_144
	v_readlane_b32 s3, v253, 50
	s_waitcnt vmcnt(0) expcnt(0) lgkmcnt(0)
	s_and_b32 s8, s2, 15
	v_mov_b32_e32 v0, s3
	ds_read_b32 v3, v0
	v_readlane_b32 s3, v253, 51
	s_waitcnt lgkmcnt(0)
	v_cmp_ne_u32_e32 vcc, 0, v3
	v_mov_b32_e32 v0, s3
	ds_read_b32 v2, v0
	s_cbranch_vccnz .LBB0_836
	s_mov_b32 s9, 1
	s_branch .LBB0_824
